# grid barrier: waiting non-leader workgroups start the XCD L2 write-back early (extra buffer_wbl2 before polling)
# baseline (speedup 1.0000x reference)
.LBB0_71:
	s_or_b64 exec, exec, s[6:7]
	v_cvt_f32_u32_e32 v4, v2
	s_waitcnt vmcnt(0)
	v_readfirstlane_b32 s0, v3
	v_sub_u32_e32 v3, 0, v2
	v_rcp_iflag_f32_e32 v4, v4
	v_add_u32_e32 v5, s0, v1
	v_mul_f32_e32 v4, 0x4f7ffffe, v4
	v_cvt_u32_f32_e32 v4, v4
	v_mul_lo_u32 v1, v3, v4
	v_mul_hi_u32 v1, v4, v1
	v_add_u32_e32 v1, v4, v1
	v_mul_hi_u32 v1, v5, v1
	v_mul_lo_u32 v3, v1, v2
	v_sub_u32_e32 v3, v5, v3
	v_add_u32_e32 v4, 1, v1
	v_sub_u32_e32 v6, v3, v2
	v_cmp_ge_u32_e32 vcc, v3, v2
	s_nop 1
	v_cndmask_b32_e32 v1, v1, v4, vcc
	v_cndmask_b32_e32 v3, v3, v6, vcc
	v_add_u32_e32 v4, 1, v1
	v_cmp_ge_u32_e32 vcc, v3, v2
	v_add_u32_e32 v3, 1, v5
	s_nop 0
	v_cndmask_b32_e32 v1, v1, v4, vcc
	v_mul_lo_u32 v4, v2, v1
	v_add_u32_e32 v2, v4, v2
	v_cmp_ne_u32_e32 vcc, v3, v2
	s_and_saveexec_b64 s[0:1], vcc
	s_xor_b64 s[6:7], exec, s[0:1]
	s_cbranch_execz .LBB0_85
	v_readlane_b32 s0, v239, 43
	s_waitcnt lgkmcnt(0)
	v_mov_b32_e32 v0, 0
	v_readlane_b32 s1, v239, 44
	s_nop 4
	buffer_wbl2 sc1
	global_load_dword v2, v0, s[0:1] sc1
	s_waitcnt vmcnt(0)
	v_cmp_eq_u32_e32 vcc, v2, v1
	s_and_saveexec_b64 s[8:9], vcc
	s_cbranch_execz .LBB0_84
	s_mov_b32 s0, 1
	s_mov_b64 s[10:11], 0
	s_branch .LBB0_75

.LBB0_303:
	s_or_b64 exec, exec, s[10:11]
	v_cvt_f32_u32_e32 v4, v2
	s_waitcnt vmcnt(0)
	v_readfirstlane_b32 s0, v3
	v_sub_u32_e32 v3, 0, v2
	v_rcp_iflag_f32_e32 v4, v4
	v_add_u32_e32 v5, s0, v1
	v_mul_f32_e32 v4, 0x4f7ffffe, v4
	v_cvt_u32_f32_e32 v4, v4
	v_mul_lo_u32 v1, v3, v4
	v_mul_hi_u32 v1, v4, v1
	v_add_u32_e32 v1, v4, v1
	v_mul_hi_u32 v1, v5, v1
	v_mul_lo_u32 v3, v1, v2
	v_sub_u32_e32 v3, v5, v3
	v_add_u32_e32 v4, 1, v1
	v_cmp_ge_u32_e32 vcc, v3, v2
	s_nop 1
	v_cndmask_b32_e32 v1, v1, v4, vcc
	v_sub_u32_e32 v4, v3, v2
	v_cndmask_b32_e32 v3, v3, v4, vcc
	v_add_u32_e32 v4, 1, v1
	v_cmp_ge_u32_e32 vcc, v3, v2
	v_add_u32_e32 v3, 1, v5
	s_nop 0
	v_cndmask_b32_e32 v1, v1, v4, vcc
	v_mul_lo_u32 v4, v2, v1
	v_add_u32_e32 v2, v4, v2
	v_cmp_ne_u32_e32 vcc, v3, v2
	s_and_saveexec_b64 s[0:1], vcc
	s_xor_b64 s[10:11], exec, s[0:1]
	s_cbranch_execz .LBB0_317
	v_readlane_b32 s0, v239, 43
	s_waitcnt lgkmcnt(0)
	v_mov_b32_e32 v0, 0
	v_readlane_b32 s1, v239, 44
	s_nop 4
	buffer_wbl2 sc1
	global_load_dword v2, v0, s[0:1] sc1
	s_waitcnt vmcnt(0)
	v_cmp_eq_u32_e32 vcc, v2, v1
	s_and_saveexec_b64 s[18:19], vcc
	s_cbranch_execz .LBB0_316
	s_mov_b32 s0, 1
	s_mov_b64 s[30:31], 0
	s_branch .LBB0_307

.LBB0_518:
	s_or_b64 exec, exec, s[18:19]
	v_cvt_f32_u32_e32 v4, v2
	s_waitcnt vmcnt(0)
	v_readfirstlane_b32 s0, v3
	v_sub_u32_e32 v3, 0, v2
	v_rcp_iflag_f32_e32 v4, v4
	v_add_u32_e32 v5, s0, v1
	v_mul_f32_e32 v4, 0x4f7ffffe, v4
	v_cvt_u32_f32_e32 v4, v4
	v_mul_lo_u32 v1, v3, v4
	v_mul_hi_u32 v1, v4, v1
	v_add_u32_e32 v1, v4, v1
	v_mul_hi_u32 v1, v5, v1
	v_mul_lo_u32 v3, v1, v2
	v_sub_u32_e32 v3, v5, v3
	v_add_u32_e32 v4, 1, v1
	v_cmp_ge_u32_e32 vcc, v3, v2
	s_nop 1
	v_cndmask_b32_e32 v1, v1, v4, vcc
	v_sub_u32_e32 v4, v3, v2
	v_cndmask_b32_e32 v3, v3, v4, vcc
	v_add_u32_e32 v4, 1, v1
	v_cmp_ge_u32_e32 vcc, v3, v2
	v_add_u32_e32 v3, 1, v5
	s_nop 0
	v_cndmask_b32_e32 v1, v1, v4, vcc
	v_mul_lo_u32 v4, v2, v1
	v_add_u32_e32 v2, v4, v2
	v_cmp_ne_u32_e32 vcc, v3, v2
	s_and_saveexec_b64 s[0:1], vcc
	s_xor_b64 s[18:19], exec, s[0:1]
	s_cbranch_execz .LBB0_532
	v_readlane_b32 s0, v239, 43
	s_waitcnt lgkmcnt(0)
	v_mov_b32_e32 v0, 0
	v_readlane_b32 s1, v239, 44
	s_nop 4
	buffer_wbl2 sc1
	global_load_dword v2, v0, s[0:1] sc1
	s_waitcnt vmcnt(0)
	v_cmp_eq_u32_e32 vcc, v2, v1
	s_and_saveexec_b64 s[36:37], vcc
	s_cbranch_execz .LBB0_531
	s_mov_b32 s0, 1
	s_mov_b64 s[38:39], 0
	s_branch .LBB0_522

.LBB0_590:
	s_or_b64 exec, exec, s[0:1]
	v_cvt_f32_u32_e32 v4, v2
	s_waitcnt vmcnt(0)
	v_readfirstlane_b32 s0, v3
	v_sub_u32_e32 v3, 0, v2
	v_rcp_iflag_f32_e32 v4, v4
	v_add_u32_e32 v5, s0, v1
	v_mul_f32_e32 v4, 0x4f7ffffe, v4
	v_cvt_u32_f32_e32 v4, v4
	v_mul_lo_u32 v1, v3, v4
	v_mul_hi_u32 v1, v4, v1
	v_add_u32_e32 v1, v4, v1
	v_mul_hi_u32 v1, v5, v1
	v_mul_lo_u32 v3, v1, v2
	v_sub_u32_e32 v3, v5, v3
	v_add_u32_e32 v4, 1, v1
	v_cmp_ge_u32_e32 vcc, v3, v2
	s_nop 1
	v_cndmask_b32_e32 v1, v1, v4, vcc
	v_sub_u32_e32 v4, v3, v2
	v_cndmask_b32_e32 v3, v3, v4, vcc
	v_add_u32_e32 v4, 1, v1
	v_cmp_ge_u32_e32 vcc, v3, v2
	v_add_u32_e32 v3, 1, v5
	s_nop 0
	v_cndmask_b32_e32 v1, v1, v4, vcc
	v_mul_lo_u32 v4, v2, v1
	v_add_u32_e32 v2, v4, v2
	v_cmp_ne_u32_e32 vcc, v3, v2
	s_and_saveexec_b64 s[0:1], vcc
	s_xor_b64 s[0:1], exec, s[0:1]
	s_cbranch_execz .LBB0_604
	v_readlane_b32 s6, v239, 43
	s_waitcnt lgkmcnt(0)
	v_mov_b32_e32 v0, 0
	v_readlane_b32 s7, v239, 44
	s_nop 4
	buffer_wbl2 sc1
	global_load_dword v2, v0, s[6:7] sc1
	s_waitcnt vmcnt(0)
	v_cmp_eq_u32_e32 vcc, v2, v1
	s_and_saveexec_b64 s[6:7], vcc
	s_cbranch_execz .LBB0_603
	s_mov_b32 s18, 1
	s_mov_b64 s[8:9], 0
	s_branch .LBB0_594
